# v83 + cmb phase software-pipelined: next item's 7 loads issued before current item's arithmetic, global_* loads
# speedup vs baseline: 1.0123x; 1.0055x over previous
; DI void phase_cmb(const Params& P) {
;     ...
;     for (int idx = blockIdx.x * NTHR + tid; idx < HT * 96; idx += gridDim.x * NTHR) {
;         const int row = idx / 96, c8 = idx % 96; const int head = c8 >> 3;
;         float l0 = pbl[((size_t)0 * HT + row) * 12 + head], l1 = pbl[((size_t)1 * HT + row) * 12 + head], l2 = pbl[((size_t)2 * HT + row) * 12 + head];
;         float mx = fmaxf(l0, fmaxf(l1, l2));
;         float w0 = __expf(l0 - mx), w1 = __expf(l1 - mx), w2 = __expf(l2 - mx);
;         const float inv = 1.f / (w0 + w1 + w2); w0 *= inv; w1 *= inv; w2 *= inv;
;         u32x4 a = *(const u32x4*)(pbo + ((size_t)0 * HT + row) * 768 + c8 * 8);
;         u32x4 b = *(const u32x4*)(pbo + ((size_t)1 * HT + row) * 768 + c8 * 8);
;         u32x4 c = *(const u32x4*)(pbo + ((size_t)2 * HT + row) * 768 + c8 * 8);
;         u32x4 z = *(const u32x4*)(Ph + (size_t)row * PO + OFF_Z + 768 + c8 * 8);
.LBB0_322:
	s_or_b64 exec, exec, s[0:1]
	v_readlane_b32 s0, v237, 12
	v_readlane_b32 s2, v237, 14
	v_readlane_b32 s3, v237, 15
	v_readlane_b32 s4, v237, 16
	v_readlane_b32 s5, v237, 17
	v_readlane_b32 s6, v237, 18
	v_readlane_b32 s7, v237, 19
	v_readlane_b32 s1, v237, 13
	s_mov_b64 s[8:9], s[60:61]
	s_mov_b64 s[2:3], s[24:25]
	s_mov_b64 s[4:5], s[38:39]
	s_mov_b64 s[6:7], s[98:99]
	s_mov_b64 s[10:11], s[28:29]
	s_waitcnt lgkmcnt(0)
	s_barrier
	v_mov_b32_e32 v2, v174
	v_readlane_b32 s0, v237, 20
	s_nop 1
	v_add_u32_e32 v0, s0, v2
	v_cmp_gt_i32_e32 vcc, s40, v0
	s_and_saveexec_b64 s[0:1], vcc
	s_cbranch_execz .LBB0_325
	s_add_u32 s4, s8, 0xcf40000
	s_addc_u32 s5, s9, 0
	s_add_u32 s6, s8, 0x8500000
	s_addc_u32 s7, s9, 0
	s_add_u32 s8, s8, 0xcd00000
	v_readlane_b32 s2, v236, 17
	s_addc_u32 s9, s9, 0
	s_mov_b64 s[10:11], 0
	v_lshl_add_u32 v2, v2, 3, s2
	s_lshl_b32 s2, s16, 3
	s_mov_b32 s3, 0x2aaaaaab
	v_mul_hi_i32 v37, v0, s3
	v_lshrrev_b32_e32 v38, 31, v37
	v_ashrrev_i32_e32 v37, 4, v37
	v_add_u32_e32 v37, v37, v38
	s_movk_i32 s3, 0xffa0
	v_mad_u64_u32 v[38:39], vcc, v37, s3, v[0:1]
	v_ashrrev_i32_e32 v38, 3, v38
	v_ashrrev_i32_e32 v39, 31, v38
	v_mad_i64_i32 v[40:41], vcc, v37, 48, s[8:9]
	v_lshl_add_u64 v[38:39], v[38:39], 2, v[40:41]
	s_mov_b32 s3, 0xc0000
	v_add_co_u32_e32 v40, vcc, s3, v38
	global_load_dword v48, v[38:39], off
	s_nop 0
	v_addc_co_u32_e32 v41, vcc, 0, v39, vcc
	global_load_dword v49, v[40:41], off
	v_add_co_u32_e32 v38, vcc, s40, v38
	s_nop 1
	v_addc_co_u32_e32 v39, vcc, 0, v39, vcc
	global_load_dword v50, v[38:39], off
	v_mov_b64_e32 v[42:43], s[4:5]
	v_mad_i64_i32 v[42:43], vcc, v37, s52, v[42:43]
	s_movk_i32 s3, 0xfd00
	v_mad_u64_u32 v[44:45], vcc, v37, s3, v[2:3]
	v_mov_b64_e32 v[46:47], s[6:7]
	v_ashrrev_i32_e32 v45, 31, v44
	v_mad_i64_i32 v[46:47], vcc, v37, s42, v[46:47]
	v_lshlrev_b64 v[44:45], 1, v[44:45]
	v_lshl_add_u64 v[46:47], v[46:47], 0, v[44:45]
	global_load_dwordx4 v[52:55], v[46:47], off
	s_mov_b32 s3, 0x1800000
	v_add_co_u32_e32 v40, vcc, s3, v46
	s_nop 1
	v_addc_co_u32_e32 v41, vcc, 0, v47, vcc
	global_load_dwordx4 v[56:59], v[40:41], off
	s_mov_b32 s3, 0x3000000
	v_add_co_u32_e32 v40, vcc, s3, v46
	s_nop 1
	v_addc_co_u32_e32 v41, vcc, 0, v47, vcc
	global_load_dwordx4 v[60:63], v[40:41], off
	v_lshl_add_u64 v[68:69], v[42:43], 0, v[44:45]
	s_movk_i32 s3, 0x2000
	v_add_co_u32_e32 v40, vcc, s3, v68
	s_nop 1
	v_addc_co_u32_e32 v41, vcc, 0, v69, vcc
	global_load_dwordx4 v[64:67], v[40:41], off offset:3328
.LBB0_324:
	s_waitcnt vmcnt(0)
	v_mov_b32_e32 v8, v48
	v_mov_b32_e32 v6, v49
	v_mov_b32_e32 v4, v50
	v_mov_b64_e32 v[10:11], v[52:53]
	v_mov_b64_e32 v[12:13], v[54:55]
	v_mov_b64_e32 v[14:15], v[56:57]
	v_mov_b64_e32 v[16:17], v[58:59]
	v_mov_b64_e32 v[18:19], v[60:61]
	v_mov_b64_e32 v[20:21], v[62:63]
	v_mov_b64_e32 v[22:23], v[64:65]
	v_mov_b64_e32 v[24:25], v[66:67]
	v_mov_b64_e32 v[26:27], v[68:69]
	v_add_u32_e32 v0, s16, v0
	v_add_u32_e32 v2, s2, v2
	s_mov_b32 s3, 0x17ffff
	v_cmp_ge_i32_e32 vcc, s3, v0
	s_and_saveexec_b64 s[12:13], vcc
	s_cbranch_execz .Lcmb_nopf
	s_mov_b32 s3, 0x2aaaaaab
	v_mul_hi_i32 v37, v0, s3
	v_lshrrev_b32_e32 v38, 31, v37
	v_ashrrev_i32_e32 v37, 4, v37
	v_add_u32_e32 v37, v37, v38
	s_movk_i32 s3, 0xffa0
	v_mad_u64_u32 v[38:39], vcc, v37, s3, v[0:1]
	v_ashrrev_i32_e32 v38, 3, v38
	v_ashrrev_i32_e32 v39, 31, v38
	v_mad_i64_i32 v[40:41], vcc, v37, 48, s[8:9]
	v_lshl_add_u64 v[38:39], v[38:39], 2, v[40:41]
	s_mov_b32 s3, 0xc0000
	v_add_co_u32_e32 v40, vcc, s3, v38
	global_load_dword v48, v[38:39], off
	s_nop 0
	v_addc_co_u32_e32 v41, vcc, 0, v39, vcc
	global_load_dword v49, v[40:41], off
	v_add_co_u32_e32 v38, vcc, s40, v38
	s_nop 1
	v_addc_co_u32_e32 v39, vcc, 0, v39, vcc
	global_load_dword v50, v[38:39], off
	v_mov_b64_e32 v[42:43], s[4:5]
	v_mad_i64_i32 v[42:43], vcc, v37, s52, v[42:43]
	s_movk_i32 s3, 0xfd00
	v_mad_u64_u32 v[44:45], vcc, v37, s3, v[2:3]
	v_mov_b64_e32 v[46:47], s[6:7]
	v_ashrrev_i32_e32 v45, 31, v44
	v_mad_i64_i32 v[46:47], vcc, v37, s42, v[46:47]
	v_lshlrev_b64 v[44:45], 1, v[44:45]
	v_lshl_add_u64 v[46:47], v[46:47], 0, v[44:45]
	global_load_dwordx4 v[52:55], v[46:47], off
	s_mov_b32 s3, 0x1800000
	v_add_co_u32_e32 v40, vcc, s3, v46
	s_nop 1
	v_addc_co_u32_e32 v41, vcc, 0, v47, vcc
	global_load_dwordx4 v[56:59], v[40:41], off
	s_mov_b32 s3, 0x3000000
	v_add_co_u32_e32 v40, vcc, s3, v46
	s_nop 1
	v_addc_co_u32_e32 v41, vcc, 0, v47, vcc
	global_load_dwordx4 v[60:63], v[40:41], off
	v_lshl_add_u64 v[68:69], v[42:43], 0, v[44:45]
	s_movk_i32 s3, 0x2000
	v_add_co_u32_e32 v40, vcc, s3, v68
	s_nop 1
	v_addc_co_u32_e32 v41, vcc, 0, v69, vcc
	global_load_dwordx4 v[64:67], v[40:41], off offset:3328
; DI unsigned pk2(float lo, float hi) { fl2_t f = {lo, hi}; bf2_t b = __builtin_convertvector(f, bf2_t); return __builtin_bit_cast(unsigned, b); }
; DI float bflo(unsigned u) { return __uint_as_float(u << 16); }
; DI float bfhi(unsigned u) { return __uint_as_float(u & 0xffff0000u); }
; DI float silu_f(float z) { return z / (1.f + __expf(-z)); }
; DI void phase_cmb(const Params& P) {
;     ...
;         float l0 = pbl[((size_t)0 * HT + row) * 12 + head], l1 = pbl[((size_t)1 * HT + row) * 12 + head], l2 = pbl[((size_t)2 * HT + row) * 12 + head];
;         float mx = fmaxf(l0, fmaxf(l1, l2));
;         float w0 = __expf(l0 - mx), w1 = __expf(l1 - mx), w2 = __expf(l2 - mx);
;         const float inv = 1.f / (w0 + w1 + w2); w0 *= inv; w1 *= inv; w2 *= inv;
;         u32x4 a = *(const u32x4*)(pbo + ((size_t)0 * HT + row) * 768 + c8 * 8);
;         u32x4 b = *(const u32x4*)(pbo + ((size_t)1 * HT + row) * 768 + c8 * 8);
;         u32x4 c = *(const u32x4*)(pbo + ((size_t)2 * HT + row) * 768 + c8 * 8);
;         u32x4 z = *(const u32x4*)(Ph + (size_t)row * PO + OFF_Z + 768 + c8 * 8);
;         u32x4 o;
; #pragma unroll
;         for (int j = 0; j < 4; ++j) {
;             float lo = (w0 * bflo(a[j]) + w1 * bflo(b[j]) + w2 * bflo(c[j])) * silu_f(bflo(z[j]));
;             float hi = (w0 * bfhi(a[j]) + w1 * bfhi(b[j]) + w2 * bfhi(c[j])) * silu_f(bfhi(z[j]));
;             o[j] = pk2(lo, hi);
;         }
;         *(u32x4*)(Ph + (size_t)row * PO + OFF_BQ + c8 * 8) = o;
.Lcmb_nopf:
	s_or_b64 exec, exec, s[12:13]
	v_max3_f32 v5, v8, v6, v4
	v_sub_f32_e32 v7, v8, v5
	v_sub_f32_e32 v6, v6, v5
	v_mul_f32_e32 v7, 0x3fb8aa3b, v7
	v_mul_f32_e32 v6, 0x3fb8aa3b, v6
	v_sub_f32_e32 v4, v4, v5
	v_exp_f32_e32 v7, v7
	v_exp_f32_e32 v6, v6
	v_mul_f32_e32 v4, 0x3fb8aa3b, v4
	v_exp_f32_e32 v4, v4
	v_add_f32_e32 v5, v7, v6
	v_add_f32_e32 v5, v4, v5
	v_div_scale_f32 v8, s[12:13], v5, v5, 1.0
	v_rcp_f32_e32 v9, v8
	s_nop 0
	v_fma_f32 v30, -v8, v9, 1.0
	v_fmac_f32_e32 v9, v30, v9
	v_div_scale_f32 v30, vcc, 1.0, v5, 1.0
	v_mul_f32_e32 v31, v30, v9
	v_fma_f32 v32, -v8, v31, v30
	v_fmac_f32_e32 v31, v32, v9
	v_fma_f32 v8, -v8, v31, v30
	v_div_fmas_f32 v8, v8, v9, v31
	v_div_fixup_f32 v8, v8, v5, 1.0
	v_pk_mul_f32 v[28:29], v[6:7], v[8:9] op_sel_hi:[1,0]
	v_mul_f32_e32 v4, v4, v8
	s_mov_b32 s3, 0x17ffff
	v_and_b32_e32 v9, 0xffff0000, v10
	v_lshlrev_b32_e32 v30, 16, v10
	v_lshlrev_b32_e32 v8, 16, v14
	v_and_b32_e32 v31, 0xffff0000, v14
	v_pk_mul_f32 v[30:31], v[28:29], v[30:31] op_sel:[1,0] op_sel_hi:[0,1]
	v_pk_fma_f32 v[8:9], v[28:29], v[8:9], v[30:31]
	v_lshlrev_b32_e32 v32, 16, v18
	v_and_b32_e32 v33, 0xffff0000, v18
	v_lshlrev_b32_e32 v3, 16, v22
	v_and_b32_e32 v5, 0xffff0000, v22
	v_mul_f32_e32 v6, 0xbfb8aa3b, v3
	v_mul_f32_e32 v7, 0xbfb8aa3b, v5
	v_exp_f32_e32 v6, v6
	v_exp_f32_e32 v7, v7
	s_nop 0
	v_pk_add_f32 v[6:7], v[6:7], 1.0 op_sel_hi:[1,0]
	s_nop 0
	v_div_scale_f32 v10, s[12:13], v7, v7, v5
	v_rcp_f32_e32 v14, v10
	s_nop 0
	v_fma_f32 v18, -v10, v14, 1.0
	v_fmac_f32_e32 v14, v18, v14
	v_div_scale_f32 v18, vcc, v5, v7, v5
	v_mul_f32_e32 v22, v18, v14
	v_fma_f32 v34, -v10, v22, v18
	v_fmac_f32_e32 v22, v34, v14
	v_fma_f32 v10, -v10, v22, v18
	v_div_fmas_f32 v10, v10, v14, v22
	v_div_fixup_f32 v7, v10, v7, v5
	v_div_scale_f32 v5, s[12:13], v6, v6, v3
	v_rcp_f32_e32 v10, v5
	s_nop 0
	v_fma_f32 v14, -v5, v10, 1.0
	v_fmac_f32_e32 v10, v14, v10
	v_div_scale_f32 v14, vcc, v3, v6, v3
	v_mul_f32_e32 v18, v14, v10
	v_fma_f32 v22, -v5, v18, v14
	v_fmac_f32_e32 v18, v22, v10
	v_fma_f32 v5, -v5, v18, v14
	v_div_fmas_f32 v5, v5, v10, v18
	v_div_fixup_f32 v6, v5, v6, v3
	v_pk_fma_f32 v[8:9], v[4:5], v[32:33], v[8:9] op_sel_hi:[0,1,1]
	v_pk_mul_f32 v[6:7], v[6:7], v[8:9]
	v_lshlrev_b32_e32 v3, 16, v23
	v_cvt_pk_bf16_f32 v6, v6, v7
	v_and_b32_e32 v5, 0xffff0000, v23
	v_mul_f32_e32 v7, 0xbfb8aa3b, v3
	v_exp_f32_e32 v8, v7
	v_mul_f32_e32 v7, 0xbfb8aa3b, v5
	v_exp_f32_e32 v9, v7
	v_lshlrev_b32_e32 v22, 16, v15
	v_and_b32_e32 v23, 0xffff0000, v11
	v_lshlrev_b32_e32 v10, 16, v11
	v_pk_add_f32 v[8:9], v[8:9], 1.0 op_sel_hi:[1,0]
	v_and_b32_e32 v11, 0xffff0000, v15
	v_div_scale_f32 v7, s[12:13], v9, v9, v5
	v_rcp_f32_e32 v18, v7
	v_lshlrev_b32_e32 v14, 16, v19
	v_and_b32_e32 v15, 0xffff0000, v19
	v_pk_mul_f32 v[10:11], v[28:29], v[10:11] op_sel:[1,0] op_sel_hi:[0,1]
	v_fma_f32 v19, -v7, v18, 1.0
	v_fmac_f32_e32 v18, v19, v18
	v_div_scale_f32 v19, vcc, v5, v9, v5
	v_mul_f32_e32 v30, v19, v18
	v_fma_f32 v31, -v7, v30, v19
	v_fmac_f32_e32 v30, v31, v18
	v_fma_f32 v7, -v7, v30, v19
	v_div_fmas_f32 v7, v7, v18, v30
	v_div_fixup_f32 v9, v7, v9, v5
	v_div_scale_f32 v5, s[12:13], v8, v8, v3
	v_rcp_f32_e32 v7, v5
	v_pk_fma_f32 v[10:11], v[28:29], v[22:23], v[10:11]
	v_fma_f32 v18, -v5, v7, 1.0
	v_fmac_f32_e32 v7, v18, v7
	v_div_scale_f32 v18, vcc, v3, v8, v3
	v_mul_f32_e32 v19, v18, v7
	v_fma_f32 v30, -v5, v19, v18
	v_fmac_f32_e32 v19, v30, v7
	v_fma_f32 v5, -v5, v19, v18
	v_div_fmas_f32 v5, v5, v7, v19
	v_div_fixup_f32 v8, v5, v8, v3
	v_pk_fma_f32 v[10:11], v[4:5], v[14:15], v[10:11] op_sel_hi:[0,1,1]
	v_pk_mul_f32 v[8:9], v[8:9], v[10:11]
	v_lshlrev_b32_e32 v3, 16, v24
	v_and_b32_e32 v5, 0xffff0000, v24
	v_cvt_pk_bf16_f32 v7, v8, v9
	v_mul_f32_e32 v8, 0xbfb8aa3b, v3
	v_mul_f32_e32 v9, 0xbfb8aa3b, v5
	v_exp_f32_e32 v8, v8
	v_exp_f32_e32 v9, v9
	v_and_b32_e32 v11, 0xffff0000, v12
	v_lshlrev_b32_e32 v14, 16, v12
	v_lshlrev_b32_e32 v10, 16, v16
	v_pk_add_f32 v[8:9], v[8:9], 1.0 op_sel_hi:[1,0]
	v_and_b32_e32 v15, 0xffff0000, v16
	v_div_scale_f32 v12, s[12:13], v9, v9, v5
	v_rcp_f32_e32 v16, v12
	v_lshlrev_b32_e32 v18, 16, v20
	v_and_b32_e32 v19, 0xffff0000, v20
	v_pk_mul_f32 v[14:15], v[28:29], v[14:15] op_sel:[1,0] op_sel_hi:[0,1]
	v_fma_f32 v20, -v12, v16, 1.0
	v_fmac_f32_e32 v16, v20, v16
	v_div_scale_f32 v20, vcc, v5, v9, v5
	v_mul_f32_e32 v22, v20, v16
	v_fma_f32 v23, -v12, v22, v20
	v_fmac_f32_e32 v22, v23, v16
	v_fma_f32 v12, -v12, v22, v20
	v_div_fmas_f32 v12, v12, v16, v22
	v_div_fixup_f32 v9, v12, v9, v5
	v_div_scale_f32 v5, s[12:13], v8, v8, v3
	v_rcp_f32_e32 v12, v5
	v_pk_fma_f32 v[10:11], v[28:29], v[10:11], v[14:15]
	v_and_b32_e32 v15, 0xffff0000, v13
	v_lshlrev_b32_e32 v14, 16, v17
	v_fma_f32 v16, -v5, v12, 1.0
	v_fmac_f32_e32 v12, v16, v12
	v_div_scale_f32 v16, vcc, v3, v8, v3
	v_mul_f32_e32 v20, v16, v12
	v_fma_f32 v22, -v5, v20, v16
	v_fmac_f32_e32 v20, v22, v12
	v_fma_f32 v5, -v5, v20, v16
	v_div_fmas_f32 v5, v5, v12, v20
	v_div_fixup_f32 v8, v5, v8, v3
	v_pk_fma_f32 v[10:11], v[4:5], v[18:19], v[10:11] op_sel_hi:[0,1,1]
	v_pk_mul_f32 v[8:9], v[8:9], v[10:11]
	v_lshlrev_b32_e32 v3, 16, v25
	v_cvt_pk_bf16_f32 v8, v8, v9
	v_and_b32_e32 v9, 0xffff0000, v25
	v_mul_f32_e32 v5, 0xbfb8aa3b, v3
	v_mul_f32_e32 v11, 0xbfb8aa3b, v9
	v_exp_f32_e32 v10, v5
	v_exp_f32_e32 v11, v11
	v_lshlrev_b32_e32 v12, 16, v13
	v_and_b32_e32 v13, 0xffff0000, v17
	v_pk_mul_f32 v[12:13], v[28:29], v[12:13] op_sel:[1,0] op_sel_hi:[0,1]
	v_pk_fma_f32 v[12:13], v[28:29], v[14:15], v[12:13]
	v_lshlrev_b32_e32 v14, 16, v21
	v_and_b32_e32 v15, 0xffff0000, v21
	v_pk_add_f32 v[10:11], v[10:11], 1.0 op_sel_hi:[1,0]
	v_pk_fma_f32 v[4:5], v[4:5], v[14:15], v[12:13] op_sel_hi:[0,1,1]
	v_div_scale_f32 v12, s[12:13], v11, v11, v9
	v_rcp_f32_e32 v13, v12
	s_nop 0
	v_fma_f32 v14, -v12, v13, 1.0
	v_fmac_f32_e32 v13, v14, v13
	v_div_scale_f32 v14, vcc, v9, v11, v9
	v_mul_f32_e32 v15, v14, v13
	v_fma_f32 v16, -v12, v15, v14
	v_fmac_f32_e32 v15, v16, v13
	v_fma_f32 v12, -v12, v15, v14
	v_div_fmas_f32 v12, v12, v13, v15
	v_div_fixup_f32 v11, v12, v11, v9
	v_div_scale_f32 v9, s[12:13], v10, v10, v3
	v_rcp_f32_e32 v12, v9
	s_nop 0
	v_fma_f32 v13, -v9, v12, 1.0
	v_fmac_f32_e32 v12, v13, v12
	v_div_scale_f32 v13, vcc, v3, v10, v3
	v_mul_f32_e32 v14, v13, v12
	v_fma_f32 v15, -v9, v14, v13
	v_fmac_f32_e32 v14, v15, v12
	v_fma_f32 v9, -v9, v14, v13
	v_div_fmas_f32 v9, v9, v12, v14
	v_div_fixup_f32 v10, v9, v10, v3
	v_pk_mul_f32 v[4:5], v[10:11], v[4:5]
	v_cmp_lt_i32_e32 vcc, s3, v0
	v_cvt_pk_bf16_f32 v9, v4, v5
	s_or_b64 s[10:11], vcc, s[10:11]
	global_store_dwordx4 v[26:27], v[6:9], off offset:2304
	s_andn2_b64 exec, exec, s[10:11]
	s_cbranch_execnz .LBB0_324
